# MLA: first 8 transposed V reads of each MFMA block issued before the block's barrier (V tile already visible)
# baseline (speedup 1.0000x reference)
.LBB0_665:
	v_add_f32_e32 v151, v18, v19
	v_lshlrev_b32_e32 v18, 1, v50
	v_and_b32_e32 v18, 32, v18
	v_and_or_b32 v18, v51, s67, v18
	v_and_b32_e32 v19, 0x100, v52
	v_fmac_f32_e32 v151, 0, v58
	v_or3_b32 v158, v18, v19, v53
	v_add_u32_e32 v187, v57, v56
	v_add_u32_e32 v188, 0, v56
	v_cmp_gt_u32_e64 s[4:5], 32, v50
	v_lshl_add_u32 v157, v54, 2, s18
	v_lshlrev_b32_e32 v156, 4, v55
	v_mov_b64_e32 v[32:33], v[16:17]
	v_mov_b64_e32 v[48:49], v[16:17]
	v_mov_b64_e32 v[64:65], v[16:17]
	s_mov_b32 s93, 1
	v_add_u32_e32 v185, s35, v158
	s_mov_b32 s95, 0x8000
	s_movk_i32 s94, 0x4000
	s_mov_b32 s8, 0
	v_mov_b64_e32 v[30:31], v[14:15]
	v_mov_b64_e32 v[28:29], v[12:13]
	v_mov_b64_e32 v[26:27], v[10:11]
	v_mov_b64_e32 v[24:25], v[8:9]
	v_mov_b64_e32 v[22:23], v[6:7]
	v_mov_b64_e32 v[20:21], v[4:5]
	v_mov_b64_e32 v[18:19], v[2:3]
	v_mov_b64_e32 v[46:47], v[14:15]
	v_mov_b64_e32 v[44:45], v[12:13]
	v_mov_b64_e32 v[42:43], v[10:11]
	v_mov_b64_e32 v[40:41], v[8:9]
	v_mov_b64_e32 v[38:39], v[6:7]
	v_mov_b64_e32 v[36:37], v[4:5]
	v_mov_b64_e32 v[34:35], v[2:3]
	v_mov_b64_e32 v[62:63], v[14:15]
	v_mov_b64_e32 v[60:61], v[12:13]
	v_mov_b64_e32 v[58:59], v[10:11]
	v_mov_b64_e32 v[56:57], v[8:9]
	v_mov_b64_e32 v[54:55], v[6:7]
	v_mov_b64_e32 v[52:53], v[4:5]
	v_mov_b64_e32 v[50:51], v[2:3]
	v_add_u32_e32 v189, v187, v160
	v_add_u32_e32 v190, v187, v162
	v_add_u32_e32 v191, v187, v164
	v_add_u32_e32 v192, v187, v166
	v_add_u32_e32 v250, s8, v185
	ds_read_b64_tr_b16 v[202:203], v250 offset:0
	ds_read_b64_tr_b16 v[204:205], v250 offset:0x800
	ds_read_b64_tr_b16 v[206:207], v250 offset:0x1000
	ds_read_b64_tr_b16 v[208:209], v250 offset:0x1800
	ds_read_b64_tr_b16 v[210:211], v250 offset:0x2000
	ds_read_b64_tr_b16 v[212:213], v250 offset:0x2800
	ds_read_b64_tr_b16 v[214:215], v250 offset:0x3000
	ds_read_b64_tr_b16 v[216:217], v250 offset:0x3800
.LBB0_666:
	s_barrier
	s_setprio 3
	s_mov_b32 s12, s94
	s_mov_b32 s94, s8
	v_add_u32_e32 v250, s94, v185
	ds_read_b128 v[66:69], v189 offset:16384
	ds_read_b128 v[70:73], v189 offset:24576
	s_waitcnt lgkmcnt(8)
	v_mfma_f32_32x32x16_bf16 v[50:65], v[130:133], v[202:205], v[50:65]
	ds_read_b64_tr_b16 v[218:219], v250 offset:0x200
	ds_read_b64_tr_b16 v[220:221], v250 offset:0xa00
	s_waitcnt lgkmcnt(8)
	v_mfma_f32_32x32x16_bf16 v[50:65], v[126:129], v[206:209], v[50:65]
	ds_read_b64_tr_b16 v[222:223], v250 offset:0x1200
	ds_read_b64_tr_b16 v[224:225], v250 offset:0x1a00
	ds_read_b128 v[194:197], v190 offset:16384
	s_waitcnt lgkmcnt(9)
	v_mfma_f32_32x32x16_bf16 v[50:65], v[122:125], v[210:213], v[50:65]
	ds_read_b64_tr_b16 v[226:227], v250 offset:0x2200
	ds_read_b64_tr_b16 v[228:229], v250 offset:0x2a00
	s_waitcnt lgkmcnt(9)
	v_mfma_f32_32x32x16_bf16 v[50:65], v[118:121], v[214:217], v[50:65]
	ds_read_b64_tr_b16 v[230:231], v250 offset:0x3200
	ds_read_b64_tr_b16 v[232:233], v250 offset:0x3a00
	ds_read_b128 v[198:201], v190 offset:24576
	s_waitcnt lgkmcnt(8)
	v_mfma_f32_32x32x16_bf16 v[34:49], v[130:133], v[218:221], v[34:49]
	ds_read_b64_tr_b16 v[202:203], v250 offset:0x400
	ds_read_b64_tr_b16 v[204:205], v250 offset:0xc00
	s_waitcnt lgkmcnt(8)
	v_mfma_f32_32x32x16_bf16 v[34:49], v[126:129], v[222:225], v[34:49]
	ds_read_b64_tr_b16 v[206:207], v250 offset:0x1400
	ds_read_b64_tr_b16 v[208:209], v250 offset:0x1c00
	ds_read_b128 v[234:237], v191 offset:16384
	s_waitcnt lgkmcnt(8)
	v_mfma_f32_32x32x16_bf16 v[34:49], v[122:125], v[226:229], v[34:49]
	ds_read_b64_tr_b16 v[210:211], v250 offset:0x2400
	ds_read_b64_tr_b16 v[212:213], v250 offset:0x2c00
	s_waitcnt lgkmcnt(8)
	v_mfma_f32_32x32x16_bf16 v[34:49], v[118:121], v[230:233], v[34:49]
	ds_read_b64_tr_b16 v[214:215], v250 offset:0x3400
	ds_read_b64_tr_b16 v[216:217], v250 offset:0x3c00
	ds_read_b128 v[238:241], v191 offset:24576
	s_waitcnt lgkmcnt(8)
	v_mfma_f32_32x32x16_bf16 v[18:33], v[130:133], v[202:205], v[18:33]
	ds_read_b64_tr_b16 v[218:219], v250 offset:0x600
	ds_read_b64_tr_b16 v[220:221], v250 offset:0xe00
	s_waitcnt lgkmcnt(8)
	v_mfma_f32_32x32x16_bf16 v[18:33], v[126:129], v[206:209], v[18:33]
	ds_read_b64_tr_b16 v[222:223], v250 offset:0x1600
	ds_read_b64_tr_b16 v[224:225], v250 offset:0x1e00
	ds_read_b128 v[242:245], v192 offset:16384
	s_waitcnt lgkmcnt(8)
	v_mfma_f32_32x32x16_bf16 v[18:33], v[122:125], v[210:213], v[18:33]
	ds_read_b64_tr_b16 v[226:227], v250 offset:0x2600
	ds_read_b64_tr_b16 v[228:229], v250 offset:0x2e00
	s_waitcnt lgkmcnt(8)
	v_mfma_f32_32x32x16_bf16 v[18:33], v[118:121], v[214:217], v[18:33]
	ds_read_b64_tr_b16 v[230:231], v250 offset:0x3600
	ds_read_b64_tr_b16 v[232:233], v250 offset:0x3e00
	ds_read_b128 v[246:249], v192 offset:24576
	s_waitcnt lgkmcnt(8)
	v_mfma_f32_32x32x16_bf16 v[2:17], v[130:133], v[218:221], v[2:17]
	s_waitcnt lgkmcnt(6)
	v_mfma_f32_32x32x16_bf16 v[2:17], v[126:129], v[222:225], v[2:17]
	v_add_u32_e32 v202, v187, v168
	ds_read_b128 v[202:205], v202 offset:16384
	v_add_u32_e32 v206, v187, v168
	ds_read_b128 v[206:209], v206 offset:24576
	s_waitcnt lgkmcnt(5)
	v_mfma_f32_32x32x16_bf16 v[2:17], v[122:125], v[226:229], v[2:17]
	s_waitcnt lgkmcnt(3)
	v_mfma_f32_32x32x16_bf16 v[2:17], v[118:121], v[230:233], v[2:17]
	v_add_u32_e32 v210, v187, v170
	ds_read_b128 v[210:213], v210 offset:16384
	v_add_u32_e32 v214, v187, v170
	ds_read_b128 v[214:217], v214 offset:24576
	v_mfma_f32_32x32x16_bf16 v[82:97], v[66:69], v[114:117], 0
	v_mfma_f32_32x32x16_bf16 v[66:81], v[70:73], v[114:117], 0
	ds_read_b128 v[218:221], v159
	v_add_u32_e32 v222, v187, v172
	ds_read_b128 v[222:225], v222 offset:16384
	v_add_u32_e32 v226, v187, v172
	ds_read_b128 v[226:229], v226 offset:24576
	v_mfma_f32_32x32x16_bf16 v[82:97], v[194:197], v[110:113], v[82:97]
	v_mfma_f32_32x32x16_bf16 v[66:81], v[198:201], v[110:113], v[66:81]
	ds_read_b128 v[230:233], v159 offset:1024
	v_add_u32_e32 v194, v187, v174
	ds_read_b128 v[194:197], v194 offset:16384
	v_add_u32_e32 v198, v187, v174
	ds_read_b128 v[198:201], v198 offset:24576
	v_mfma_f32_32x32x16_bf16 v[82:97], v[234:237], v[106:109], v[82:97]
	v_mfma_f32_32x32x16_bf16 v[66:81], v[238:241], v[106:109], v[66:81]
	ds_read_b128 v[234:237], v159 offset:2048
	v_add_u32_e32 v238, v188, v177
	ds_read_b128 v[238:241], v238 offset:40960
	v_mfma_f32_32x32x16_bf16 v[82:97], v[242:245], v[102:105], v[82:97]
	s_waitcnt lgkmcnt(12)
	v_mfma_f32_32x32x16_bf16 v[66:81], v[246:249], v[102:105], v[66:81]
	v_add_u32_e32 v242, v188, v177
	ds_read_b128 v[242:245], v242 offset:45056
	ds_read_b128 v[246:249], v159 offset:3072
	s_waitcnt lgkmcnt(13)
	v_mfma_f32_32x32x16_bf16 v[82:97], v[202:205], v[98:101], v[82:97]
	s_waitcnt lgkmcnt(12)
	v_mfma_f32_32x32x16_bf16 v[66:81], v[206:209], v[98:101], v[66:81]
	v_add_u32_e32 v202, v188, v179
	ds_read_b128 v[202:205], v202 offset:40960
	v_add_u32_e32 v206, v188, v179
	ds_read_b128 v[206:209], v206 offset:45056
	s_waitcnt lgkmcnt(11)
	v_mfma_f32_32x32x16_bf16 v[82:97], v[210:213], v[218:221], v[82:97]
	v_mfma_f32_32x32x16_bf16 v[66:81], v[214:217], v[218:221], v[66:81]
	ds_read_b128 v[210:213], v159 offset:4096
	v_add_u32_e32 v214, v188, v181
	ds_read_b128 v[214:217], v214 offset:40960
	v_add_u32_e32 v218, v188, v181
	ds_read_b128 v[218:221], v218 offset:45056
	s_waitcnt lgkmcnt(11)
	v_mfma_f32_32x32x16_bf16 v[82:97], v[222:225], v[230:233], v[82:97]
	v_mfma_f32_32x32x16_bf16 v[66:81], v[226:229], v[230:233], v[66:81]
	ds_read_b128 v[222:225], v159 offset:5120
	v_add_u32_e32 v226, v188, v183
	ds_read_b128 v[226:229], v226 offset:40960
	v_add_u32_e32 v230, v188, v183
	ds_read_b128 v[230:233], v230 offset:45056
	s_waitcnt lgkmcnt(11)
	v_mfma_f32_32x32x16_bf16 v[82:97], v[194:197], v[234:237], v[82:97]
	v_mfma_f32_32x32x16_bf16 v[66:81], v[198:201], v[234:237], v[66:81]
	ds_read_b128 v[194:197], v159 offset:6144
	s_waitcnt lgkmcnt(9)
	v_mfma_f32_32x32x16_bf16 v[82:97], v[238:241], v[246:249], v[82:97]
	v_mfma_f32_32x32x16_bf16 v[66:81], v[242:245], v[246:249], v[66:81]
	s_waitcnt lgkmcnt(6)
	v_mfma_f32_32x32x16_bf16 v[82:97], v[202:205], v[210:213], v[82:97]
	v_mfma_f32_32x32x16_bf16 v[66:81], v[206:209], v[210:213], v[66:81]
	s_waitcnt lgkmcnt(3)
	v_mfma_f32_32x32x16_bf16 v[82:97], v[214:217], v[222:225], v[82:97]
	v_mfma_f32_32x32x16_bf16 v[66:81], v[218:221], v[222:225], v[66:81]
	s_waitcnt lgkmcnt(0)
	v_mfma_f32_32x32x16_bf16 v[82:97], v[226:229], v[194:197], v[82:97]
	v_mfma_f32_32x32x16_bf16 v[66:81], v[230:233], v[194:197], v[66:81]
	s_and_b64 vcc, exec, s[6:7]
	s_cbranch_vccnz .LBB0_668
	s_waitcnt vmcnt(0)

.LBB0_676:
	v_cndmask_b32_e64 v186, v118, v186, s[8:9]
	v_sub_f32_e32 v82, v82, v186
	v_sub_f32_e32 v83, v83, v186
	v_exp_f32_e32 v82, v82
	v_sub_f32_e32 v84, v84, v186
	v_exp_f32_e32 v83, v83
	v_sub_f32_e32 v85, v85, v186
	v_exp_f32_e32 v84, v84
	v_sub_f32_e32 v86, v86, v186
	v_exp_f32_e32 v85, v85
	v_sub_f32_e32 v87, v87, v186
	v_exp_f32_e32 v86, v86
	v_add_f32_e32 v118, 0, v82
	v_sub_f32_e32 v88, v88, v186
	v_exp_f32_e32 v87, v87
	v_add_f32_e32 v118, v83, v118
	v_sub_f32_e32 v89, v89, v186
	v_exp_f32_e32 v88, v88
	v_add_f32_e32 v118, v84, v118
	v_sub_f32_e32 v90, v90, v186
	v_exp_f32_e32 v89, v89
	v_add_f32_e32 v118, v85, v118
	v_sub_f32_e32 v91, v91, v186
	v_exp_f32_e32 v90, v90
	v_add_f32_e32 v118, v86, v118
	v_sub_f32_e32 v92, v92, v186
	v_exp_f32_e32 v91, v91
	v_add_f32_e32 v118, v87, v118
	v_sub_f32_e32 v93, v93, v186
	v_exp_f32_e32 v92, v92
	v_add_f32_e32 v118, v88, v118
	v_sub_f32_e32 v94, v94, v186
	v_exp_f32_e32 v93, v93
	v_add_f32_e32 v118, v89, v118
	v_sub_f32_e32 v95, v95, v186
	v_exp_f32_e32 v94, v94
	v_add_f32_e32 v118, v90, v118
	v_sub_f32_e32 v96, v96, v186
	v_exp_f32_e32 v95, v95
	v_add_f32_e32 v118, v91, v118
	v_sub_f32_e32 v97, v97, v186
	v_exp_f32_e32 v96, v96
	v_add_f32_e32 v118, v92, v118
	v_sub_f32_e32 v66, v66, v186
	v_exp_f32_e32 v97, v97
	v_add_f32_e32 v118, v93, v118
	v_sub_f32_e32 v67, v67, v186
	v_exp_f32_e32 v66, v66
	v_add_f32_e32 v118, v94, v118
	v_sub_f32_e32 v68, v68, v186
	v_exp_f32_e32 v67, v67
	v_add_f32_e32 v118, v95, v118
	v_sub_f32_e32 v69, v69, v186
	v_exp_f32_e32 v68, v68
	v_add_f32_e32 v118, v96, v118
	v_sub_f32_e32 v70, v70, v186
	v_exp_f32_e32 v69, v69
	v_add_f32_e32 v118, v97, v118
	v_sub_f32_e32 v71, v71, v186
	v_exp_f32_e32 v70, v70
	v_add_f32_e32 v118, v66, v118
	v_sub_f32_e32 v72, v72, v186
	v_exp_f32_e32 v71, v71
	v_add_f32_e32 v118, v67, v118
	v_sub_f32_e32 v73, v73, v186
	v_exp_f32_e32 v72, v72
	v_add_f32_e32 v118, v68, v118
	v_sub_f32_e32 v74, v74, v186
	v_exp_f32_e32 v73, v73
	v_add_f32_e32 v118, v69, v118
	v_sub_f32_e32 v75, v75, v186
	v_exp_f32_e32 v74, v74
	v_add_f32_e32 v118, v70, v118
	v_sub_f32_e32 v76, v76, v186
	v_exp_f32_e32 v75, v75
	v_add_f32_e32 v118, v71, v118
	v_sub_f32_e32 v77, v77, v186
	v_exp_f32_e32 v76, v76
	v_add_f32_e32 v118, v72, v118
	v_sub_f32_e32 v78, v78, v186
	v_exp_f32_e32 v77, v77
	v_add_f32_e32 v118, v73, v118
	v_sub_f32_e32 v79, v79, v186
	v_exp_f32_e32 v78, v78
	v_add_f32_e32 v118, v74, v118
	v_sub_f32_e32 v80, v80, v186
	v_exp_f32_e32 v79, v79
	v_add_f32_e32 v118, v75, v118
	v_sub_f32_e32 v81, v81, v186
	v_exp_f32_e32 v80, v80
	v_add_f32_e32 v118, v76, v118
	v_exp_f32_e32 v81, v81
	v_add_f32_e32 v118, v77, v118
	v_add_f32_e32 v118, v78, v118
	v_add_f32_e32 v118, v79, v118
	v_add_f32_e32 v118, v80, v118
	v_add_f32_e32 v202, v81, v118
	v_mov_b32_e32 v203, v202
	s_nop 1
	v_permlane32_swap_b32_e32 v202, v203
	s_and_b64 vcc, exec, s[2:3]
	v_cvt_pk_bf16_f32 v130, v82, v83
	v_cvt_pk_bf16_f32 v131, v84, v85
	v_cvt_pk_bf16_f32 v132, v86, v87
	v_cvt_pk_bf16_f32 v133, v88, v89
	v_cvt_pk_bf16_f32 v126, v90, v91
	v_cvt_pk_bf16_f32 v127, v92, v93
	v_cvt_pk_bf16_f32 v128, v94, v95
	v_cvt_pk_bf16_f32 v129, v96, v97
	v_cvt_pk_bf16_f32 v122, v66, v67
	v_cvt_pk_bf16_f32 v123, v68, v69
	v_cvt_pk_bf16_f32 v124, v70, v71
	v_cvt_pk_bf16_f32 v125, v72, v73
	v_cvt_pk_bf16_f32 v118, v74, v75
	v_cvt_pk_bf16_f32 v119, v76, v77
	v_cvt_pk_bf16_f32 v120, v78, v79
	v_cvt_pk_bf16_f32 v121, v80, v81
	v_add_u32_e32 v252, s12, v185
	ds_read_b64_tr_b16 v[204:205], v252 offset:0
	ds_read_b64_tr_b16 v[206:207], v252 offset:0x800
	ds_read_b64_tr_b16 v[208:209], v252 offset:0x1000
	ds_read_b64_tr_b16 v[210:211], v252 offset:0x1800
	ds_read_b64_tr_b16 v[212:213], v252 offset:0x2000
	ds_read_b64_tr_b16 v[214:215], v252 offset:0x2800
	ds_read_b64_tr_b16 v[216:217], v252 offset:0x3000
	ds_read_b64_tr_b16 v[218:219], v252 offset:0x3800
	s_cbranch_vccnz .LBB0_678
	s_waitcnt vmcnt(0)
.LBB0_678:
	s_barrier
	s_setprio 3
	v_add_u32_e32 v252, s12, v185
	ds_read_b128 v[66:69], v161
	ds_read_b128 v[70:73], v161 offset:8192
	s_waitcnt lgkmcnt(8)
	v_mfma_f32_32x32x16_bf16 v[50:65], v[130:133], v[204:207], v[50:65]
	ds_read_b64_tr_b16 v[220:221], v252 offset:0x200
	ds_read_b64_tr_b16 v[222:223], v252 offset:0xa00
	s_waitcnt lgkmcnt(8)
	v_mfma_f32_32x32x16_bf16 v[50:65], v[126:129], v[208:211], v[50:65]
	ds_read_b64_tr_b16 v[224:225], v252 offset:0x1200
	ds_read_b64_tr_b16 v[226:227], v252 offset:0x1a00
	ds_read_b128 v[236:239], v163
	s_waitcnt lgkmcnt(9)
	v_mfma_f32_32x32x16_bf16 v[50:65], v[122:125], v[212:215], v[50:65]
	ds_read_b64_tr_b16 v[228:229], v252 offset:0x2200
	ds_read_b64_tr_b16 v[230:231], v252 offset:0x2a00
	s_waitcnt lgkmcnt(9)
	v_mfma_f32_32x32x16_bf16 v[50:65], v[118:121], v[216:219], v[50:65]
	ds_read_b64_tr_b16 v[232:233], v252 offset:0x3200
	ds_read_b64_tr_b16 v[234:235], v252 offset:0x3a00
	ds_read_b128 v[240:243], v163 offset:8192
	s_waitcnt lgkmcnt(8)
	v_mfma_f32_32x32x16_bf16 v[34:49], v[130:133], v[220:223], v[34:49]
	ds_read_b64_tr_b16 v[204:205], v252 offset:0x400
	ds_read_b64_tr_b16 v[206:207], v252 offset:0xc00
	s_waitcnt lgkmcnt(8)
	v_mfma_f32_32x32x16_bf16 v[34:49], v[126:129], v[224:227], v[34:49]
	ds_read_b64_tr_b16 v[208:209], v252 offset:0x1400
	ds_read_b64_tr_b16 v[210:211], v252 offset:0x1c00
	ds_read_b128 v[244:247], v165
	s_waitcnt lgkmcnt(8)
	v_mfma_f32_32x32x16_bf16 v[34:49], v[122:125], v[228:231], v[34:49]
	ds_read_b64_tr_b16 v[212:213], v252 offset:0x2400
	ds_read_b64_tr_b16 v[214:215], v252 offset:0x2c00
	s_waitcnt lgkmcnt(8)
	v_mfma_f32_32x32x16_bf16 v[34:49], v[118:121], v[232:235], v[34:49]
	ds_read_b64_tr_b16 v[216:217], v252 offset:0x3400
	ds_read_b64_tr_b16 v[218:219], v252 offset:0x3c00
	ds_read_b128 v[248:251], v165 offset:8192
	s_waitcnt lgkmcnt(8)
	v_mfma_f32_32x32x16_bf16 v[18:33], v[130:133], v[204:207], v[18:33]
	ds_read_b64_tr_b16 v[220:221], v252 offset:0x600
	ds_read_b64_tr_b16 v[222:223], v252 offset:0xe00
	s_waitcnt lgkmcnt(8)
	v_mfma_f32_32x32x16_bf16 v[18:33], v[126:129], v[208:211], v[18:33]
	ds_read_b64_tr_b16 v[224:225], v252 offset:0x1600
	ds_read_b64_tr_b16 v[226:227], v252 offset:0x1e00
	s_waitcnt lgkmcnt(7)
	v_mfma_f32_32x32x16_bf16 v[18:33], v[122:125], v[212:215], v[18:33]
	ds_read_b64_tr_b16 v[228:229], v252 offset:0x2600
	ds_read_b64_tr_b16 v[230:231], v252 offset:0x2e00
	s_waitcnt lgkmcnt(7)
	v_mfma_f32_32x32x16_bf16 v[18:33], v[118:121], v[216:219], v[18:33]
	ds_read_b64_tr_b16 v[232:233], v252 offset:0x3600
	ds_read_b64_tr_b16 v[234:235], v252 offset:0x3e00
	s_waitcnt lgkmcnt(6)
	v_mfma_f32_32x32x16_bf16 v[2:17], v[130:133], v[220:223], v[2:17]
	s_waitcnt lgkmcnt(4)
	v_mfma_f32_32x32x16_bf16 v[2:17], v[126:129], v[224:227], v[2:17]
	ds_read_b128 v[204:207], v167
	ds_read_b128 v[208:211], v167 offset:8192
	s_waitcnt lgkmcnt(4)
	v_mfma_f32_32x32x16_bf16 v[2:17], v[122:125], v[228:231], v[2:17]
	s_waitcnt lgkmcnt(2)
	v_mfma_f32_32x32x16_bf16 v[2:17], v[118:121], v[232:235], v[2:17]
	ds_read_b128 v[212:215], v169
	ds_read_b128 v[216:219], v169 offset:8192
	v_mfma_f32_32x32x16_bf16 v[82:97], v[66:69], v[114:117], 0
	v_mfma_f32_32x32x16_bf16 v[66:81], v[70:73], v[114:117], 0
	ds_read_b128 v[220:223], v171
	ds_read_b128 v[224:227], v171 offset:8192
	ds_read_b128 v[228:231], v159
	v_mfma_f32_32x32x16_bf16 v[82:97], v[236:239], v[110:113], v[82:97]
	v_mfma_f32_32x32x16_bf16 v[66:81], v[240:243], v[110:113], v[66:81]
	ds_read_b128 v[232:235], v173
	ds_read_b128 v[236:239], v173 offset:8192
	ds_read_b128 v[240:243], v159 offset:1024
	v_mfma_f32_32x32x16_bf16 v[82:97], v[244:247], v[106:109], v[82:97]
	v_mfma_f32_32x32x16_bf16 v[66:81], v[248:251], v[106:109], v[66:81]
	ds_read_b128 v[244:247], v175
	ds_read_b128 v[248:251], v175 offset:8192
	s_waitcnt lgkmcnt(11)
	v_mfma_f32_32x32x16_bf16 v[82:97], v[204:207], v[102:105], v[82:97]
	s_waitcnt lgkmcnt(10)
	v_mfma_f32_32x32x16_bf16 v[66:81], v[208:211], v[102:105], v[66:81]
	ds_read_b128 v[204:207], v159 offset:2048
	ds_read_b128 v[208:211], v178 offset:32768
	s_waitcnt lgkmcnt(11)
	v_mfma_f32_32x32x16_bf16 v[82:97], v[212:215], v[98:101], v[82:97]
	s_waitcnt lgkmcnt(10)
	v_mfma_f32_32x32x16_bf16 v[66:81], v[216:219], v[98:101], v[66:81]
	ds_read_b128 v[212:215], v178 offset:36864
	ds_read_b128 v[216:219], v159 offset:3072
	s_waitcnt lgkmcnt(9)
	v_mfma_f32_32x32x16_bf16 v[82:97], v[220:223], v[228:231], v[82:97]
	v_mfma_f32_32x32x16_bf16 v[66:81], v[224:227], v[228:231], v[66:81]
	ds_read_b128 v[220:223], v180 offset:32768
	ds_read_b128 v[224:227], v180 offset:36864
	ds_read_b128 v[228:231], v159 offset:4096
	s_waitcnt lgkmcnt(9)
	v_mfma_f32_32x32x16_bf16 v[82:97], v[232:235], v[240:243], v[82:97]
	v_mfma_f32_32x32x16_bf16 v[66:81], v[236:239], v[240:243], v[66:81]
	ds_read_b128 v[232:235], v182 offset:32768
	ds_read_b128 v[236:239], v182 offset:36864
	ds_read_b128 v[240:243], v159 offset:5120
	s_waitcnt lgkmcnt(9)
	v_mfma_f32_32x32x16_bf16 v[82:97], v[244:247], v[204:207], v[82:97]
	v_mfma_f32_32x32x16_bf16 v[66:81], v[248:251], v[204:207], v[66:81]
	ds_read_b128 v[244:247], v184 offset:32768
	ds_read_b128 v[248:251], v184 offset:36864
	ds_read_b128 v[204:207], v159 offset:6144
	s_waitcnt lgkmcnt(9)
	v_mfma_f32_32x32x16_bf16 v[82:97], v[208:211], v[216:219], v[82:97]
	v_mfma_f32_32x32x16_bf16 v[66:81], v[212:215], v[216:219], v[66:81]
	s_waitcnt lgkmcnt(6)
	v_mfma_f32_32x32x16_bf16 v[82:97], v[220:223], v[228:231], v[82:97]
	v_mfma_f32_32x32x16_bf16 v[66:81], v[224:227], v[228:231], v[66:81]
	s_waitcnt lgkmcnt(3)
	v_mfma_f32_32x32x16_bf16 v[82:97], v[232:235], v[240:243], v[82:97]
	v_mfma_f32_32x32x16_bf16 v[66:81], v[236:239], v[240:243], v[66:81]
	s_waitcnt lgkmcnt(0)
	v_mfma_f32_32x32x16_bf16 v[82:97], v[244:247], v[204:207], v[82:97]
	v_mfma_f32_32x32x16_bf16 v[66:81], v[248:251], v[204:207], v[66:81]
	s_and_b64 vcc, exec, s[6:7]
	s_cbranch_vccnz .LBB0_680
	s_waitcnt vmcnt(0)

.LBB0_690:
	v_add_f32_e32 v68, v202, v203
	v_fmac_f32_e32 v68, v151, v201
	v_add_f32_e32 v151, v66, v67
	v_fmac_f32_e32 v151, v68, v204
	s_add_i32 s93, s93, 2
	s_and_b64 vcc, exec, s[56:57]
	s_cbranch_vccnz .Lrot_mla_exit
	s_mov_b32 s8, s95
	s_mov_b32 s95, s12
	v_add_u32_e32 v189, v187, v160
	v_add_u32_e32 v190, v187, v162
	v_add_u32_e32 v191, v187, v164
	v_add_u32_e32 v192, v187, v166
	v_add_u32_e32 v250, s8, v185
	ds_read_b64_tr_b16 v[202:203], v250 offset:0
	ds_read_b64_tr_b16 v[204:205], v250 offset:0x800
	ds_read_b64_tr_b16 v[206:207], v250 offset:0x1000
	ds_read_b64_tr_b16 v[208:209], v250 offset:0x1800
	ds_read_b64_tr_b16 v[210:211], v250 offset:0x2000
	ds_read_b64_tr_b16 v[212:213], v250 offset:0x2800
	ds_read_b64_tr_b16 v[214:215], v250 offset:0x3000
	ds_read_b64_tr_b16 v[216:217], v250 offset:0x3800
	s_branch .LBB0_666
